# MLA attention loop: last QK MFMA writes the score block directly (srcC = running accumulator), 16 v_mov_b64 per iteration removed, on top of v3
# baseline (speedup 1.0000x reference)
.LBB0_436:
	v_add3_u32 v198, s20, v180, v182
	ds_read_b128 v[82:85], v198
	ds_read_b128 v[186:189], v198 offset:32
	s_mulk_i32 s24, 0x4800
	v_add_u32_e32 v221, s24, v185
	v_sub_f32_e32 v202, v2, v184
	s_waitcnt lgkmcnt(1)
	v_mfma_f32_32x32x16_bf16 v[82:97], v[82:85], v[98:101], 0
	v_sub_f32_e32 v203, v3, v184
	v_sub_f32_e32 v204, v4, v184
	v_sub_f32_e32 v205, v5, v184
	v_sub_f32_e32 v206, v6, v184
	v_sub_f32_e32 v207, v7, v184
	v_sub_f32_e32 v208, v8, v184
	v_sub_f32_e32 v209, v9, v184
	s_waitcnt lgkmcnt(0)
	v_mfma_f32_32x32x16_bf16 v[82:97], v[186:189], v[102:105], v[82:97]
	ds_read_b128 v[186:189], v198 offset:64
	ds_read_b128 v[190:193], v198 offset:96
	v_exp_f32_e32 v217, v202
	v_exp_f32_e32 v218, v203
	v_exp_f32_e32 v219, v204
	v_exp_f32_e32 v220, v205
	v_exp_f32_e32 v206, v206
	v_exp_f32_e32 v207, v207
	s_waitcnt lgkmcnt(1)
	v_mfma_f32_32x32x16_bf16 v[82:97], v[186:189], v[106:109], v[82:97]
	v_exp_f32_e32 v208, v208
	v_exp_f32_e32 v209, v209
	v_sub_f32_e32 v210, v10, v184
	v_sub_f32_e32 v211, v11, v184
	v_sub_f32_e32 v212, v12, v184
	v_sub_f32_e32 v213, v13, v184
	v_sub_f32_e32 v214, v14, v184
	s_waitcnt lgkmcnt(0)
	v_mfma_f32_32x32x16_bf16 v[82:97], v[190:193], v[110:113], v[82:97]
	ds_read_b128 v[186:189], v198 offset:128
	ds_read_b128 v[190:193], v198 offset:160
	v_sub_f32_e32 v215, v15, v184
	v_sub_f32_e32 v216, v16, v184
	v_exp_f32_e32 v210, v210
	v_exp_f32_e32 v211, v211
	v_exp_f32_e32 v212, v212
	v_exp_f32_e32 v213, v213
	s_waitcnt lgkmcnt(1)
	v_mfma_f32_32x32x16_bf16 v[82:97], v[186:189], v[114:117], v[82:97]
	ds_read_b128 v[186:189], v198 offset:192
	v_exp_f32_e32 v214, v214
	v_exp_f32_e32 v215, v215
	v_exp_f32_e32 v216, v216
	v_max_f32_e32 v3, v3, v3
	v_max_f32_e32 v2, v2, v2
	v_max_f32_e32 v2, v2, v3
	s_waitcnt lgkmcnt(1)
	v_mfma_f32_32x32x16_bf16 v[82:97], v[190:193], v[118:121], v[82:97]
	ds_read_b128 v[190:193], v198 offset:224
	v_max3_f32 v2, v2, v4, v5
	v_max3_f32 v2, v2, v6, v7
	v_max3_f32 v2, v2, v8, v9
	v_max3_f32 v6, v2, v10, v11
	v_max3_f32 v6, v6, v12, v13
	v_max3_f32 v6, v6, v14, v15
	s_waitcnt lgkmcnt(1)
	v_mfma_f32_32x32x16_bf16 v[82:97], v[186:189], v[122:125], v[82:97]
	ds_read_b128 v[186:189], v198 offset:256
	v_max3_f32 v10, v6, v16, v17
	v_add_f32_e32 v6, 0, v217
	v_add_f32_e32 v12, v218, v6
	ds_bpermute_b32 v11, v178, v10
	s_waitcnt lgkmcnt(2)
	v_mfma_f32_32x32x16_bf16 v[82:97], v[190:193], v[126:129], v[82:97]
	ds_read_b128 v[190:193], v198 offset:288
	ds_read_b128 v[194:197], v198 offset:320
	ds_read_b128 v[198:201], v198 offset:352
	s_waitcnt lgkmcnt(4)
	v_mfma_f32_32x32x16_bf16 v[82:97], v[186:189], v[130:133], v[82:97]
	ds_read_b128 v[186:189], v221 offset:51264
	s_waitcnt lgkmcnt(3)
	v_mfma_f32_32x32x16_bf16 v[82:97], v[190:193], v[134:137], v[82:97]
	ds_read_b128 v[190:193], v221 offset:51296
	s_waitcnt lgkmcnt(3)
	v_mfma_f32_32x32x16_bf16 v[82:97], v[194:197], v[138:141], v[82:97]
	v_cvt_pk_bf16_f32 v194, v217, v218
	v_cvt_pk_bf16_f32 v195, v219, v220
	v_cvt_pk_bf16_f32 v196, v206, v207
	v_cvt_pk_bf16_f32 v197, v208, v209
	s_waitcnt lgkmcnt(1)
	s_nop 0
	v_mfma_f32_32x32x16_bf16 v[18:33], v[186:189], v[194:197], v[18:33]
	v_sub_f32_e32 v186, v17, v184
	v_exp_f32_e32 v222, v186
	v_cvt_pk_bf16_f32 v186, v210, v211
	v_cvt_pk_bf16_f32 v187, v212, v213
	v_cvt_pk_bf16_f32 v188, v214, v215
	v_cvt_pk_bf16_f32 v189, v216, v222
	s_waitcnt lgkmcnt(0)
	s_nop 0
	v_mfma_f32_32x32x16_bf16 v[18:33], v[190:193], v[186:189], v[18:33]
	ds_read_b128 v[190:193], v221 offset:55872
	ds_read_b128 v[202:205], v221 offset:55904
	ds_read_b128 v[2:5], v221 offset:60512
	ds_read_b128 v[6:9], v221 offset:65088
	s_waitcnt lgkmcnt(3)
	v_mfma_f32_32x32x16_bf16 v[34:49], v[190:193], v[194:197], v[34:49]
	ds_read_b128 v[190:193], v221 offset:60480
	s_waitcnt lgkmcnt(0)
	v_mfma_f32_32x32x16_bf16 v[50:65], v[190:193], v[194:197], v[50:65]
	v_mfma_f32_32x32x16_bf16 v[50:65], v[2:5], v[186:189], v[50:65]
	v_add_f32_e32 v2, v219, v12
	v_add_f32_e32 v2, v220, v2
	v_add_f32_e32 v2, v206, v2
	v_add_f32_e32 v2, v207, v2
	v_add_f32_e32 v2, v208, v2
	v_add_f32_e32 v12, v209, v2
	ds_read_b128 v[2:5], v221 offset:65120
	v_mfma_f32_32x32x16_bf16 v[66:81], v[6:9], v[194:197], v[66:81]
	v_add_f32_e32 v6, v210, v12
	v_add_f32_e32 v6, v211, v6
	v_add_f32_e32 v6, v212, v6
	v_add_f32_e32 v6, v213, v6
	v_add_f32_e32 v6, v214, v6
	v_add_f32_e32 v6, v215, v6
	v_add_f32_e32 v6, v216, v6
	s_waitcnt lgkmcnt(0)
	v_mfma_f32_32x32x16_bf16 v[66:81], v[2:5], v[186:189], v[66:81]
	v_add_f32_e32 v2, v222, v6
	v_max_f32_e32 v3, v11, v11
	v_add_f32_e32 v183, v183, v2
	v_mfma_f32_32x32x16_bf16 v[34:49], v[202:205], v[186:189], v[34:49]
	v_max_f32_e32 v186, v10, v3
	v_sub_f32_e32 v202, v186, v184
	v_cmp_lt_f32_e32 vcc, s2, v202
	v_mfma_f32_32x32x16_bf16 v[2:17], v[198:201], v[142:145], v[82:97]
	s_cbranch_vccz .LBB0_438
	v_max_f32_e32 v202, v202, v202
	v_max_f32_e32 v203, 0, v202
	v_exp_f32_e64 v202, -v203
	v_add_f32_e32 v184, v184, v203
	v_mul_f32_e32 v183, v183, v202
	v_pk_mul_f32 v[32:33], v[202:203], v[32:33] op_sel_hi:[0,1]
	v_pk_mul_f32 v[30:31], v[202:203], v[30:31] op_sel_hi:[0,1]
	v_pk_mul_f32 v[28:29], v[202:203], v[28:29] op_sel_hi:[0,1]
	v_pk_mul_f32 v[26:27], v[202:203], v[26:27] op_sel_hi:[0,1]
	v_pk_mul_f32 v[24:25], v[202:203], v[24:25] op_sel_hi:[0,1]
	v_pk_mul_f32 v[22:23], v[202:203], v[22:23] op_sel_hi:[0,1]
	v_pk_mul_f32 v[20:21], v[202:203], v[20:21] op_sel_hi:[0,1]
	v_pk_mul_f32 v[18:19], v[202:203], v[18:19] op_sel_hi:[0,1]
	v_pk_mul_f32 v[48:49], v[202:203], v[48:49] op_sel_hi:[0,1]
	v_pk_mul_f32 v[46:47], v[202:203], v[46:47] op_sel_hi:[0,1]
	v_pk_mul_f32 v[44:45], v[202:203], v[44:45] op_sel_hi:[0,1]
	v_pk_mul_f32 v[42:43], v[202:203], v[42:43] op_sel_hi:[0,1]
	v_pk_mul_f32 v[40:41], v[202:203], v[40:41] op_sel_hi:[0,1]
	v_pk_mul_f32 v[38:39], v[202:203], v[38:39] op_sel_hi:[0,1]
	v_pk_mul_f32 v[36:37], v[202:203], v[36:37] op_sel_hi:[0,1]
	v_pk_mul_f32 v[34:35], v[202:203], v[34:35] op_sel_hi:[0,1]
	v_pk_mul_f32 v[64:65], v[202:203], v[64:65] op_sel_hi:[0,1]
	v_pk_mul_f32 v[62:63], v[202:203], v[62:63] op_sel_hi:[0,1]
	v_pk_mul_f32 v[60:61], v[202:203], v[60:61] op_sel_hi:[0,1]
	v_pk_mul_f32 v[58:59], v[202:203], v[58:59] op_sel_hi:[0,1]
	v_pk_mul_f32 v[56:57], v[202:203], v[56:57] op_sel_hi:[0,1]
	v_pk_mul_f32 v[54:55], v[202:203], v[54:55] op_sel_hi:[0,1]
	v_pk_mul_f32 v[52:53], v[202:203], v[52:53] op_sel_hi:[0,1]
	v_pk_mul_f32 v[50:51], v[202:203], v[50:51] op_sel_hi:[0,1]
	v_pk_mul_f32 v[80:81], v[202:203], v[80:81] op_sel_hi:[0,1]
	v_pk_mul_f32 v[78:79], v[202:203], v[78:79] op_sel_hi:[0,1]
	v_pk_mul_f32 v[76:77], v[202:203], v[76:77] op_sel_hi:[0,1]
	v_pk_mul_f32 v[74:75], v[202:203], v[74:75] op_sel_hi:[0,1]
	v_pk_mul_f32 v[72:73], v[202:203], v[72:73] op_sel_hi:[0,1]
	v_pk_mul_f32 v[70:71], v[202:203], v[70:71] op_sel_hi:[0,1]
	v_pk_mul_f32 v[68:69], v[202:203], v[68:69] op_sel_hi:[0,1]
	v_pk_mul_f32 v[66:67], v[202:203], v[66:67] op_sel_hi:[0,1]

.LBB0_443:
	v_add3_u32 v198, s20, v180, v182
	ds_read_b128 v[82:85], v198 offset:12800
	ds_read_b128 v[186:189], v198 offset:12832
	s_mul_i32 s12, s19, 0x4800
	v_add_u32_e32 v221, s12, v185
	v_sub_f32_e32 v202, v2, v184
	s_waitcnt lgkmcnt(1)
	v_mfma_f32_32x32x16_bf16 v[82:97], v[82:85], v[98:101], 0
	v_sub_f32_e32 v203, v3, v184
	v_sub_f32_e32 v204, v4, v184
	v_sub_f32_e32 v205, v5, v184
	v_sub_f32_e32 v206, v6, v184
	v_sub_f32_e32 v207, v7, v184
	v_sub_f32_e32 v208, v8, v184
	v_sub_f32_e32 v209, v9, v184
	s_waitcnt lgkmcnt(0)
	v_mfma_f32_32x32x16_bf16 v[82:97], v[186:189], v[102:105], v[82:97]
	ds_read_b128 v[186:189], v198 offset:12864
	ds_read_b128 v[190:193], v198 offset:12896
	v_exp_f32_e32 v217, v202
	v_exp_f32_e32 v218, v203
	v_exp_f32_e32 v219, v204
	v_exp_f32_e32 v220, v205
	v_exp_f32_e32 v206, v206
	v_exp_f32_e32 v207, v207
	s_waitcnt lgkmcnt(1)
	v_mfma_f32_32x32x16_bf16 v[82:97], v[186:189], v[106:109], v[82:97]
	v_exp_f32_e32 v208, v208
	v_exp_f32_e32 v209, v209
	v_sub_f32_e32 v210, v10, v184
	v_sub_f32_e32 v211, v11, v184
	v_sub_f32_e32 v212, v12, v184
	v_sub_f32_e32 v213, v13, v184
	v_sub_f32_e32 v214, v14, v184
	s_waitcnt lgkmcnt(0)
	v_mfma_f32_32x32x16_bf16 v[82:97], v[190:193], v[110:113], v[82:97]
	ds_read_b128 v[186:189], v198 offset:12928
	ds_read_b128 v[190:193], v198 offset:12960
	v_sub_f32_e32 v215, v15, v184
	v_sub_f32_e32 v216, v16, v184
	v_exp_f32_e32 v210, v210
	v_exp_f32_e32 v211, v211
	v_exp_f32_e32 v212, v212
	v_exp_f32_e32 v213, v213
	s_waitcnt lgkmcnt(1)
	v_mfma_f32_32x32x16_bf16 v[82:97], v[186:189], v[114:117], v[82:97]
	ds_read_b128 v[186:189], v198 offset:12992
	v_exp_f32_e32 v214, v214
	v_exp_f32_e32 v215, v215
	v_exp_f32_e32 v216, v216
	v_max_f32_e32 v3, v3, v3
	v_max_f32_e32 v2, v2, v2
	v_max_f32_e32 v2, v2, v3
	s_waitcnt lgkmcnt(1)
	v_mfma_f32_32x32x16_bf16 v[82:97], v[190:193], v[118:121], v[82:97]
	ds_read_b128 v[190:193], v198 offset:13024
	v_max3_f32 v2, v2, v4, v5
	v_max3_f32 v2, v2, v6, v7
	v_max3_f32 v2, v2, v8, v9
	v_max3_f32 v6, v2, v10, v11
	v_max3_f32 v6, v6, v12, v13
	v_max3_f32 v6, v6, v14, v15
	s_waitcnt lgkmcnt(1)
	v_mfma_f32_32x32x16_bf16 v[82:97], v[186:189], v[122:125], v[82:97]
	ds_read_b128 v[186:189], v198 offset:13056
	v_max3_f32 v10, v6, v16, v17
	v_add_f32_e32 v6, 0, v217
	v_add_f32_e32 v12, v218, v6
	ds_bpermute_b32 v11, v178, v10
	s_waitcnt lgkmcnt(2)
	v_mfma_f32_32x32x16_bf16 v[82:97], v[190:193], v[126:129], v[82:97]
	ds_read_b128 v[190:193], v198 offset:13088
	ds_read_b128 v[194:197], v198 offset:13120
	ds_read_b128 v[198:201], v198 offset:13152
	s_waitcnt lgkmcnt(4)
	v_mfma_f32_32x32x16_bf16 v[82:97], v[186:189], v[130:133], v[82:97]
	ds_read_b128 v[186:189], v221 offset:51200
	s_waitcnt lgkmcnt(3)
	v_mfma_f32_32x32x16_bf16 v[82:97], v[190:193], v[134:137], v[82:97]
	ds_read_b128 v[190:193], v221 offset:51232
	s_waitcnt lgkmcnt(3)
	v_mfma_f32_32x32x16_bf16 v[82:97], v[194:197], v[138:141], v[82:97]
	v_cvt_pk_bf16_f32 v194, v217, v218
	v_cvt_pk_bf16_f32 v195, v219, v220
	v_cvt_pk_bf16_f32 v196, v206, v207
	v_cvt_pk_bf16_f32 v197, v208, v209
	s_waitcnt lgkmcnt(1)
	s_nop 0
	v_mfma_f32_32x32x16_bf16 v[18:33], v[186:189], v[194:197], v[18:33]
	v_sub_f32_e32 v186, v17, v184
	v_exp_f32_e32 v222, v186
	v_cvt_pk_bf16_f32 v186, v210, v211
	v_cvt_pk_bf16_f32 v187, v212, v213
	v_cvt_pk_bf16_f32 v188, v214, v215
	v_cvt_pk_bf16_f32 v189, v216, v222
	s_waitcnt lgkmcnt(0)
	s_nop 0
	v_mfma_f32_32x32x16_bf16 v[18:33], v[190:193], v[186:189], v[18:33]
	ds_read_b128 v[190:193], v221 offset:55808
	ds_read_b128 v[202:205], v221 offset:55840
	ds_read_b128 v[2:5], v221 offset:60448
	ds_read_b128 v[6:9], v221 offset:65024
	s_waitcnt lgkmcnt(3)
	v_mfma_f32_32x32x16_bf16 v[34:49], v[190:193], v[194:197], v[34:49]
	ds_read_b128 v[190:193], v221 offset:60416
	s_waitcnt lgkmcnt(0)
	v_mfma_f32_32x32x16_bf16 v[50:65], v[190:193], v[194:197], v[50:65]
	v_mfma_f32_32x32x16_bf16 v[50:65], v[2:5], v[186:189], v[50:65]
	v_add_f32_e32 v2, v219, v12
	v_add_f32_e32 v2, v220, v2
	v_add_f32_e32 v2, v206, v2
	v_add_f32_e32 v2, v207, v2
	v_add_f32_e32 v2, v208, v2
	v_add_f32_e32 v12, v209, v2
	ds_read_b128 v[2:5], v221 offset:65056
	v_mfma_f32_32x32x16_bf16 v[66:81], v[6:9], v[194:197], v[66:81]
	v_add_f32_e32 v6, v210, v12
	v_add_f32_e32 v6, v211, v6
	v_add_f32_e32 v6, v212, v6
	v_add_f32_e32 v6, v213, v6
	v_add_f32_e32 v6, v214, v6
	v_add_f32_e32 v6, v215, v6
	v_add_f32_e32 v6, v216, v6
	s_waitcnt lgkmcnt(0)
	v_mfma_f32_32x32x16_bf16 v[66:81], v[2:5], v[186:189], v[66:81]
	v_add_f32_e32 v2, v222, v6
	v_max_f32_e32 v3, v11, v11
	v_add_f32_e32 v183, v183, v2
	v_mfma_f32_32x32x16_bf16 v[34:49], v[202:205], v[186:189], v[34:49]
	v_max_f32_e32 v186, v10, v3
	v_sub_f32_e32 v202, v186, v184
	v_cmp_lt_f32_e32 vcc, s2, v202
	v_mfma_f32_32x32x16_bf16 v[2:17], v[198:201], v[142:145], v[82:97]
	s_cbranch_vccz .LBB0_445
	v_max_f32_e32 v202, v202, v202
	v_max_f32_e32 v203, 0, v202
	v_exp_f32_e64 v202, -v203
	v_add_f32_e32 v184, v184, v203
	v_mul_f32_e32 v183, v183, v202
	v_pk_mul_f32 v[32:33], v[32:33], v[202:203] op_sel_hi:[1,0]
	v_pk_mul_f32 v[30:31], v[30:31], v[202:203] op_sel_hi:[1,0]
	v_pk_mul_f32 v[28:29], v[28:29], v[202:203] op_sel_hi:[1,0]
	v_pk_mul_f32 v[26:27], v[26:27], v[202:203] op_sel_hi:[1,0]
	v_pk_mul_f32 v[24:25], v[24:25], v[202:203] op_sel_hi:[1,0]
	v_pk_mul_f32 v[22:23], v[22:23], v[202:203] op_sel_hi:[1,0]
	v_pk_mul_f32 v[20:21], v[20:21], v[202:203] op_sel_hi:[1,0]
	v_pk_mul_f32 v[18:19], v[18:19], v[202:203] op_sel_hi:[1,0]
	v_pk_mul_f32 v[48:49], v[202:203], v[48:49] op_sel_hi:[0,1]
	v_pk_mul_f32 v[46:47], v[202:203], v[46:47] op_sel_hi:[0,1]
	v_pk_mul_f32 v[44:45], v[202:203], v[44:45] op_sel_hi:[0,1]
	v_pk_mul_f32 v[42:43], v[202:203], v[42:43] op_sel_hi:[0,1]
	v_pk_mul_f32 v[40:41], v[202:203], v[40:41] op_sel_hi:[0,1]
	v_pk_mul_f32 v[38:39], v[202:203], v[38:39] op_sel_hi:[0,1]
	v_pk_mul_f32 v[36:37], v[202:203], v[36:37] op_sel_hi:[0,1]
	v_pk_mul_f32 v[34:35], v[202:203], v[34:35] op_sel_hi:[0,1]
	v_pk_mul_f32 v[64:65], v[202:203], v[64:65] op_sel_hi:[0,1]
	v_pk_mul_f32 v[62:63], v[202:203], v[62:63] op_sel_hi:[0,1]
	v_pk_mul_f32 v[60:61], v[202:203], v[60:61] op_sel_hi:[0,1]
	v_pk_mul_f32 v[58:59], v[202:203], v[58:59] op_sel_hi:[0,1]
	v_pk_mul_f32 v[56:57], v[202:203], v[56:57] op_sel_hi:[0,1]
	v_pk_mul_f32 v[54:55], v[202:203], v[54:55] op_sel_hi:[0,1]
	v_pk_mul_f32 v[52:53], v[202:203], v[52:53] op_sel_hi:[0,1]
	v_pk_mul_f32 v[50:51], v[202:203], v[50:51] op_sel_hi:[0,1]
	v_pk_mul_f32 v[80:81], v[202:203], v[80:81] op_sel_hi:[0,1]
	v_pk_mul_f32 v[78:79], v[202:203], v[78:79] op_sel_hi:[0,1]
	v_pk_mul_f32 v[76:77], v[202:203], v[76:77] op_sel_hi:[0,1]
	v_pk_mul_f32 v[74:75], v[202:203], v[74:75] op_sel_hi:[0,1]
	v_pk_mul_f32 v[72:73], v[202:203], v[72:73] op_sel_hi:[0,1]
	v_pk_mul_f32 v[70:71], v[202:203], v[70:71] op_sel_hi:[0,1]
	v_pk_mul_f32 v[68:69], v[202:203], v[68:69] op_sel_hi:[0,1]
	v_pk_mul_f32 v[66:67], v[202:203], v[66:67] op_sel_hi:[0,1]
